# prescale row loop: the eight nontemporal row loads issued together instead of load-wait-compute eight times (same summation order); on top of v49
# baseline (speedup 1.0000x reference)
; __device__ __forceinline__ void prescale_phase(const float* srcC, const float* srcL, const float* g, const float* modl, int iscale, bf16_t* U, unsigned long long* ssq, int gw, int ngw, int lane) {
;     ...
;     for (int m = gw; m < MT; m += ngw) {
;         const bool isc = m < MC; const int v = isc ? 4 : ((m - MC) >> 13);
;         if (v != cv) { cv = v; const f32x4* sc = (const f32x4*)(modl + (size_t)v * (NMOD * DM) + iscale * DM) + lane; const f32x4* gp = (const f32x4*)g + lane;
; #pragma unroll
;             for (int j = 0; j < 8; ++j) cf[j] = gp[64 * j] * (sc[64 * j] + 1.0f); }
;         const f32x4* xr = (const f32x4*)(isc ? srcC + (size_t)m * DM : srcL + (size_t)(m - MC) * DM) + lane;
;         f32x4 x[8]; float ss = 0.f;
; #pragma unroll
;         for (int j = 0; j < 8; ++j) { x[j] = __builtin_nontemporal_load(xr + 64 * j); ss += (x[j].x * x[j].x + x[j].y * x[j].y) + (x[j].z * x[j].z + x[j].w * x[j].w); }
;         ss = wave_sum(ss);
;         if (lane == 0) ssq[m] = (unsigned long long)(ss * pg8::SSQ_SCALE);
.LBB0_153:
	s_and_b64 s[10:11], s[40:41], exec
	s_cselect_b32 s11, s61, 0
	s_cselect_b32 s10, s60, s9
	s_cselect_b32 s9, s57, s35
	s_cselect_b32 s12, s56, s34
	s_lshl_b64 s[10:11], s[10:11], 13
	s_add_u32 s40, s12, s10
	s_addc_u32 s41, s9, s11
	v_lshl_add_u64 v[50:51], s[40:41], 0, v[174:175]
	s_movk_i32 s9, 0x1000
	v_add_co_u32_e32 v62, vcc, s9, v50
	s_nop 1
	v_addc_co_u32_e32 v63, vcc, 0, v51, vcc
	global_load_dwordx4 v[34:37], v174, s[40:41] nt
	global_load_dwordx4 v[38:41], v174, s[40:41] offset:1024 nt
	global_load_dwordx4 v[42:45], v174, s[40:41] offset:2048 nt
	global_load_dwordx4 v[46:49], v174, s[40:41] offset:3072 nt
	global_load_dwordx4 v[50:53], v[62:63], off nt
	global_load_dwordx4 v[54:57], v[62:63], off offset:1024 nt
	global_load_dwordx4 v[58:61], v[62:63], off offset:2048 nt
	global_load_dwordx4 v[62:65], v[62:63], off offset:3072 nt
	s_waitcnt vmcnt(7)
	v_mul_f32_e32 v85, v35, v35
	v_mul_f32_e32 v86, v37, v37
	v_fmac_f32_e32 v85, v34, v34
	v_fmac_f32_e32 v86, v36, v36
	v_add_f32_e32 v84, v85, v86
	s_waitcnt vmcnt(6)
	v_mul_f32_e32 v85, v39, v39
	v_mul_f32_e32 v86, v41, v41
	v_fmac_f32_e32 v85, v38, v38
	v_fmac_f32_e32 v86, v40, v40
	v_add_f32_e32 v85, v85, v86
	v_add_f32_e32 v84, v84, v85
	s_waitcnt vmcnt(5)
	v_mul_f32_e32 v85, v43, v43
	v_mul_f32_e32 v86, v45, v45
	v_fmac_f32_e32 v85, v42, v42
	v_fmac_f32_e32 v86, v44, v44
	v_add_f32_e32 v85, v85, v86
	v_add_f32_e32 v84, v84, v85
	s_waitcnt vmcnt(4)
	v_mul_f32_e32 v85, v47, v47
	v_mul_f32_e32 v86, v49, v49
	v_fmac_f32_e32 v85, v46, v46
	v_fmac_f32_e32 v86, v48, v48
	v_add_f32_e32 v85, v85, v86
	v_add_f32_e32 v84, v84, v85
	s_waitcnt vmcnt(3)
	v_mul_f32_e32 v85, v51, v51
	v_mul_f32_e32 v86, v53, v53
	v_fmac_f32_e32 v85, v50, v50
	v_fmac_f32_e32 v86, v52, v52
	v_add_f32_e32 v85, v85, v86
	v_add_f32_e32 v84, v84, v85
	s_waitcnt vmcnt(2)
	v_mul_f32_e32 v85, v55, v55
	v_mul_f32_e32 v86, v57, v57
	v_fmac_f32_e32 v85, v54, v54
	v_fmac_f32_e32 v86, v56, v56
	v_add_f32_e32 v85, v85, v86
	v_add_f32_e32 v84, v84, v85
	s_waitcnt vmcnt(1)
	v_mul_f32_e32 v85, v59, v59
	v_mul_f32_e32 v86, v61, v61
	v_fmac_f32_e32 v85, v58, v58
	v_fmac_f32_e32 v86, v60, v60
	v_add_f32_e32 v85, v85, v86
	v_add_f32_e32 v84, v84, v85
	s_waitcnt vmcnt(0)
	v_mul_f32_e32 v85, v63, v63
	v_mul_f32_e32 v86, v65, v65
	v_fmac_f32_e32 v85, v62, v62
	v_fmac_f32_e32 v86, v64, v64
	v_add_f32_e32 v85, v85, v86
	v_add_f32_e32 v84, v84, v85
	ds_bpermute_b32 v85, v78, v84
	s_waitcnt lgkmcnt(0)
	v_add_f32_e32 v84, v84, v85
	ds_bpermute_b32 v85, v79, v84
	s_waitcnt lgkmcnt(0)
	v_add_f32_e32 v84, v84, v85
	ds_bpermute_b32 v85, v80, v84
	s_waitcnt lgkmcnt(0)
	v_add_f32_e32 v84, v84, v85
	ds_bpermute_b32 v85, v81, v84
	s_waitcnt lgkmcnt(0)
	v_add_f32_e32 v84, v84, v85
	ds_bpermute_b32 v85, v82, v84
	s_waitcnt lgkmcnt(0)
	v_add_f32_e32 v84, v84, v85
	ds_bpermute_b32 v85, v83, v84
	s_and_saveexec_b64 s[40:41], s[38:39]
	s_cbranch_execz .LBB0_150
	s_waitcnt lgkmcnt(0)
	v_add_f32_e32 v84, v84, v85
	v_mul_f32_e32 v84, 0x49800000, v84
	v_trunc_f32_e32 v84, v84
	v_mul_f32_e32 v85, 0x2f800000, v84
	v_floor_f32_e32 v85, v85
	v_fmac_f32_e32 v84, 0xcf800000, v85
	v_cvt_u32_f32_e32 v84, v84
	v_cvt_u32_f32_e32 v85, v85
	s_add_u32 s10, s58, s5
	s_addc_u32 s11, s59, s7
	global_store_dwordx2 v175, v[84:85], s[10:11]
	s_branch .LBB0_150
